# peel first K-loop iteration of P1/P5/P6 with SrcC=0 (accumulator zeroing removed) on top of v9
# baseline (speedup 1.0000x reference)
.LBB0_177:
	s_ashr_i32 s29, s28, 31
	s_lshl_b64 s[38:39], s[28:29], 19
	s_add_u32 s38, s84, s38
	s_addc_u32 s39, s85, s39
	s_and_b64 s[40:41], s[36:37], exec
	s_cselect_b32 s29, s39, s1
	s_cselect_b32 s62, s38, s0
	s_ashr_i32 s35, s34, 31
	s_lshl_b64 s[40:41], s[34:35], 19
	s_add_u32 s40, s16, s40
	s_addc_u32 s41, s17, s41
	s_and_b64 s[46:47], s[36:37], exec
	s_cselect_b32 s63, s41, s45
	s_cselect_b32 s64, s40, s44
	s_lshl_b32 s35, s30, 8
	s_add_u32 s65, s44, 0x100
	v_mov_b32_e32 v2, 0
	v_or_b32_e32 v134, s35, v172
	v_lshl_add_u64 v[130:131], s[0:1], 0, v[148:149]
	v_lshl_add_u64 v[132:133], s[0:1], 0, v[150:151]
	s_addc_u32 s66, s45, 0
	s_mov_b32 s67, -2
	s_mov_b64 s[30:31], 0
	v_add_u32_e32 v135, s60, v171
	s_waitcnt lgkmcnt(0)
	ds_read_b128 v[160:163], v135
	ds_read_b128 v[164:167], v135 offset:1024
	ds_read_b128 v[178:181], v135 offset:2048
	ds_read_b128 v[182:185], v135 offset:3072
	v_add_u32_e32 v135, s61, v171
	s_add_u32 s44, s0, s30
	ds_read_b128 v[186:189], v135
	ds_read_b128 v[190:193], v135 offset:1024
	ds_read_b128 v[194:197], v135 offset:2048
	ds_read_b128 v[198:201], v135 offset:3072
	s_addc_u32 s45, s1, s31
	s_add_u32 s44, s44, 0x100
	s_addc_u32 s45, s45, 0
	s_add_u32 s72, s65, s30
	s_addc_u32 s73, s66, s31
	s_cmpk_eq_i32 s30, 0x700
	s_cselect_b32 s47, s29, s45
	s_cselect_b32 s46, s62, s44
	s_cselect_b32 s45, s63, s73
	s_cselect_b32 s44, s64, s72
	v_lshl_add_u64 v[136:137], v[130:131], 0, s[30:31]
	s_add_i32 m0, s43, 0xc000
	ds_read_b128 v[202:205], v176
	ds_read_b128 v[206:209], v176 offset:1024
	ds_read_b128 v[210:213], v176 offset:2048
	ds_read_b128 v[214:217], v176 offset:3072
	ds_read_b128 v[218:221], v176 offset:4096
	ds_read_b128 v[222:225], v176 offset:5120
	ds_read_b128 v[226:229], v176 offset:6144
	ds_read_b128 v[230:233], v176 offset:7168
	global_load_lds_dwordx4 v[136:137], off
	v_lshl_add_u64 v[136:137], v[132:133], 0, s[30:31]
	s_add_i32 m0, s43, 0xe000
	s_nop 0
	global_load_lds_dwordx4 v[136:137], off
	s_waitcnt vmcnt(8)
	s_waitcnt lgkmcnt(0)
	s_barrier
	s_setprio 1
	v_mfma_f32_16x16x32_bf16 v[126:129], v[160:163], v[202:205], 0
	v_mfma_f32_16x16x32_bf16 v[122:125], v[178:181], v[202:205], 0
	v_mfma_f32_16x16x32_bf16 v[110:113], v[160:163], v[210:213], 0
	v_mfma_f32_16x16x32_bf16 v[106:109], v[178:181], v[210:213], 0
	v_mfma_f32_16x16x32_bf16 v[94:97], v[160:163], v[218:221], 0
	v_mfma_f32_16x16x32_bf16 v[90:93], v[178:181], v[218:221], 0
	v_mfma_f32_16x16x32_bf16 v[78:81], v[160:163], v[226:229], 0
	v_mfma_f32_16x16x32_bf16 v[74:77], v[178:181], v[226:229], 0
	v_mfma_f32_16x16x32_bf16 v[126:129], v[164:167], v[206:209], v[126:129]
	v_mfma_f32_16x16x32_bf16 v[122:125], v[182:185], v[206:209], v[122:125]
	v_mfma_f32_16x16x32_bf16 v[110:113], v[164:167], v[214:217], v[110:113]
	v_mfma_f32_16x16x32_bf16 v[106:109], v[182:185], v[214:217], v[106:109]
	v_mfma_f32_16x16x32_bf16 v[94:97], v[164:167], v[222:225], v[94:97]
	v_mfma_f32_16x16x32_bf16 v[90:93], v[182:185], v[222:225], v[90:93]
	v_mfma_f32_16x16x32_bf16 v[78:81], v[164:167], v[230:233], v[78:81]
	v_mfma_f32_16x16x32_bf16 v[74:77], v[182:185], v[230:233], v[74:77]
	v_mfma_f32_16x16x32_bf16 v[118:121], v[186:189], v[202:205], 0
	v_mfma_f32_16x16x32_bf16 v[114:117], v[194:197], v[202:205], 0
	v_mfma_f32_16x16x32_bf16 v[102:105], v[186:189], v[210:213], 0
	v_mfma_f32_16x16x32_bf16 v[98:101], v[194:197], v[210:213], 0
	v_mfma_f32_16x16x32_bf16 v[86:89], v[186:189], v[218:221], 0
	v_mfma_f32_16x16x32_bf16 v[82:85], v[194:197], v[218:221], 0
	v_mfma_f32_16x16x32_bf16 v[70:73], v[186:189], v[226:229], 0
	v_mfma_f32_16x16x32_bf16 v[66:69], v[194:197], v[226:229], 0
	v_mfma_f32_16x16x32_bf16 v[118:121], v[190:193], v[206:209], v[118:121]
	v_mfma_f32_16x16x32_bf16 v[114:117], v[198:201], v[206:209], v[114:117]
	v_mfma_f32_16x16x32_bf16 v[102:105], v[190:193], v[214:217], v[102:105]
	v_mfma_f32_16x16x32_bf16 v[98:101], v[198:201], v[214:217], v[98:101]
	s_setprio 2
	s_barrier
	v_mfma_f32_16x16x32_bf16 v[86:89], v[190:193], v[222:225], v[86:89]
	v_mfma_f32_16x16x32_bf16 v[82:85], v[198:201], v[222:225], v[82:85]
	v_mfma_f32_16x16x32_bf16 v[70:73], v[190:193], v[230:233], v[70:73]
	v_mfma_f32_16x16x32_bf16 v[66:69], v[198:201], v[230:233], v[66:69]
	s_setprio 0
	s_nop 0
	s_add_i32 s72, s60, s33
	v_lshl_add_u64 v[136:137], s[44:45], 0, v[140:141]
	s_mov_b32 m0, s72
	ds_read_b128 v[202:205], v176 offset:16384
	ds_read_b128 v[206:209], v176 offset:17408
	ds_read_b128 v[210:213], v176 offset:18432
	ds_read_b128 v[214:217], v176 offset:19456
	ds_read_b128 v[218:221], v176 offset:20480
	ds_read_b128 v[222:225], v176 offset:21504
	ds_read_b128 v[226:229], v176 offset:22528
	ds_read_b128 v[230:233], v176 offset:23552
	global_load_lds_dwordx4 v[136:137], off
	s_add_i32 m0, s72, 0x2000
	s_add_u32 s72, s44, 0x40000
	v_lshl_add_u64 v[168:169], s[44:45], 0, v[144:145]
	s_addc_u32 s73, s45, 0
	s_add_i32 s74, s61, s33
	global_load_lds_dwordx4 v[168:169], off
	v_lshl_add_u64 v[234:235], s[72:73], 0, v[140:141]
	s_mov_b32 m0, s74
	v_lshl_add_u64 v[236:237], s[46:47], 0, v[142:143]
	global_load_lds_dwordx4 v[234:235], off
	v_lshl_add_u64 v[234:235], s[72:73], 0, v[144:145]
	s_add_i32 m0, s74, 0x2000
	s_nop 0
	global_load_lds_dwordx4 v[234:235], off
	v_lshl_add_u64 v[234:235], s[46:47], 0, v[138:139]
	s_mov_b32 m0, s43
	s_nop 0
	global_load_lds_dwordx4 v[234:235], off
	s_mov_b32 m0, s54
	s_nop 0
	global_load_lds_dwordx4 v[236:237], off
	s_waitcnt vmcnt(8)
	s_waitcnt lgkmcnt(0)
	s_barrier
	s_setprio 1
	v_mfma_f32_16x16x32_bf16 v[62:65], v[160:163], v[202:205], 0
	v_mfma_f32_16x16x32_bf16 v[58:61], v[178:181], v[202:205], 0
	v_mfma_f32_16x16x32_bf16 v[46:49], v[160:163], v[210:213], 0
	v_mfma_f32_16x16x32_bf16 v[42:45], v[178:181], v[210:213], 0
	v_mfma_f32_16x16x32_bf16 v[30:33], v[160:163], v[218:221], 0
	v_mfma_f32_16x16x32_bf16 v[26:29], v[178:181], v[218:221], 0
	v_mfma_f32_16x16x32_bf16 v[14:17], v[160:163], v[226:229], 0
	v_mfma_f32_16x16x32_bf16 v[10:13], v[178:181], v[226:229], 0
	v_mfma_f32_16x16x32_bf16 v[62:65], v[164:167], v[206:209], v[62:65]
	v_mfma_f32_16x16x32_bf16 v[58:61], v[182:185], v[206:209], v[58:61]
	v_mfma_f32_16x16x32_bf16 v[46:49], v[164:167], v[214:217], v[46:49]
	v_mfma_f32_16x16x32_bf16 v[42:45], v[182:185], v[214:217], v[42:45]
	v_mfma_f32_16x16x32_bf16 v[30:33], v[164:167], v[222:225], v[30:33]
	v_mfma_f32_16x16x32_bf16 v[26:29], v[182:185], v[222:225], v[26:29]
	v_mfma_f32_16x16x32_bf16 v[14:17], v[164:167], v[230:233], v[14:17]
	v_mfma_f32_16x16x32_bf16 v[10:13], v[182:185], v[230:233], v[10:13]
	v_mfma_f32_16x16x32_bf16 v[54:57], v[186:189], v[202:205], 0
	v_mfma_f32_16x16x32_bf16 v[50:53], v[194:197], v[202:205], 0
	v_mfma_f32_16x16x32_bf16 v[38:41], v[186:189], v[210:213], 0
	v_mfma_f32_16x16x32_bf16 v[34:37], v[194:197], v[210:213], 0
	v_mfma_f32_16x16x32_bf16 v[22:25], v[186:189], v[218:221], 0
	v_mfma_f32_16x16x32_bf16 v[18:21], v[194:197], v[218:221], 0
	v_mfma_f32_16x16x32_bf16 v[6:9], v[186:189], v[226:229], 0
	v_mfma_f32_16x16x32_bf16 v[2:5], v[194:197], v[226:229], 0
	v_mfma_f32_16x16x32_bf16 v[54:57], v[190:193], v[206:209], v[54:57]
	v_mfma_f32_16x16x32_bf16 v[50:53], v[198:201], v[206:209], v[50:53]
	v_mfma_f32_16x16x32_bf16 v[38:41], v[190:193], v[214:217], v[38:41]
	v_mfma_f32_16x16x32_bf16 v[34:37], v[198:201], v[214:217], v[34:37]
	s_setprio 2
	s_barrier
	v_mfma_f32_16x16x32_bf16 v[22:25], v[190:193], v[222:225], v[22:25]
	v_mfma_f32_16x16x32_bf16 v[18:21], v[198:201], v[222:225], v[18:21]
	v_mfma_f32_16x16x32_bf16 v[6:9], v[190:193], v[230:233], v[6:9]
	v_mfma_f32_16x16x32_bf16 v[2:5], v[198:201], v[230:233], v[2:5]
	s_setprio 0
	s_nop 0
	s_add_i32 s72, 0, 0x18000
	v_add_u32_e32 v135, s72, v171
	s_add_i32 s73, 0, 0x1c000
	ds_read_b128 v[160:163], v135
	ds_read_b128 v[164:167], v135 offset:1024
	ds_read_b128 v[178:181], v135 offset:2048
	ds_read_b128 v[182:185], v135 offset:3072
	v_add_u32_e32 v135, s73, v171
	ds_read_b128 v[186:189], v135
	ds_read_b128 v[190:193], v135 offset:1024
	ds_read_b128 v[194:197], v135 offset:2048
	ds_read_b128 v[198:201], v135 offset:3072
	s_add_u32 s46, s46, 0x40000
	s_addc_u32 s47, s47, 0
	s_mov_b32 m0, s55
	v_lshl_add_u64 v[238:239], s[46:47], 0, v[138:139]
	ds_read_b128 v[202:205], v176 offset:32768
	ds_read_b128 v[206:209], v176 offset:33792
	ds_read_b128 v[210:213], v176 offset:34816
	ds_read_b128 v[214:217], v176 offset:35840
	ds_read_b128 v[218:221], v176 offset:36864
	ds_read_b128 v[222:225], v176 offset:37888
	ds_read_b128 v[226:229], v176 offset:38912
	ds_read_b128 v[230:233], v176 offset:39936
	global_load_lds_dwordx4 v[238:239], off
	v_lshl_add_u64 v[238:239], s[46:47], 0, v[142:143]
	s_mov_b32 m0, s56
	s_nop 0
	global_load_lds_dwordx4 v[238:239], off
	s_waitcnt vmcnt(8)
	s_waitcnt lgkmcnt(0)
	s_barrier
	s_setprio 1
	v_mfma_f32_16x16x32_bf16 v[126:129], v[160:163], v[202:205], v[126:129]
	v_mfma_f32_16x16x32_bf16 v[122:125], v[178:181], v[202:205], v[122:125]
	v_mfma_f32_16x16x32_bf16 v[110:113], v[160:163], v[210:213], v[110:113]
	v_mfma_f32_16x16x32_bf16 v[106:109], v[178:181], v[210:213], v[106:109]
	v_mfma_f32_16x16x32_bf16 v[94:97], v[160:163], v[218:221], v[94:97]
	v_mfma_f32_16x16x32_bf16 v[90:93], v[178:181], v[218:221], v[90:93]
	v_mfma_f32_16x16x32_bf16 v[78:81], v[160:163], v[226:229], v[78:81]
	v_mfma_f32_16x16x32_bf16 v[74:77], v[178:181], v[226:229], v[74:77]
	v_mfma_f32_16x16x32_bf16 v[126:129], v[164:167], v[206:209], v[126:129]
	v_mfma_f32_16x16x32_bf16 v[122:125], v[182:185], v[206:209], v[122:125]
	v_mfma_f32_16x16x32_bf16 v[110:113], v[164:167], v[214:217], v[110:113]
	v_mfma_f32_16x16x32_bf16 v[106:109], v[182:185], v[214:217], v[106:109]
	v_mfma_f32_16x16x32_bf16 v[94:97], v[164:167], v[222:225], v[94:97]
	v_mfma_f32_16x16x32_bf16 v[90:93], v[182:185], v[222:225], v[90:93]
	v_mfma_f32_16x16x32_bf16 v[78:81], v[164:167], v[230:233], v[78:81]
	v_mfma_f32_16x16x32_bf16 v[74:77], v[182:185], v[230:233], v[74:77]
	v_mfma_f32_16x16x32_bf16 v[118:121], v[186:189], v[202:205], v[118:121]
	v_mfma_f32_16x16x32_bf16 v[114:117], v[194:197], v[202:205], v[114:117]
	v_mfma_f32_16x16x32_bf16 v[102:105], v[186:189], v[210:213], v[102:105]
	v_mfma_f32_16x16x32_bf16 v[98:101], v[194:197], v[210:213], v[98:101]
	v_mfma_f32_16x16x32_bf16 v[86:89], v[186:189], v[218:221], v[86:89]
	v_mfma_f32_16x16x32_bf16 v[82:85], v[194:197], v[218:221], v[82:85]
	v_mfma_f32_16x16x32_bf16 v[70:73], v[186:189], v[226:229], v[70:73]
	v_mfma_f32_16x16x32_bf16 v[66:69], v[194:197], v[226:229], v[66:69]
	v_mfma_f32_16x16x32_bf16 v[118:121], v[190:193], v[206:209], v[118:121]
	v_mfma_f32_16x16x32_bf16 v[114:117], v[198:201], v[206:209], v[114:117]
	v_mfma_f32_16x16x32_bf16 v[102:105], v[190:193], v[214:217], v[102:105]
	v_mfma_f32_16x16x32_bf16 v[98:101], v[198:201], v[214:217], v[98:101]
	s_setprio 2
	s_barrier
	v_mfma_f32_16x16x32_bf16 v[86:89], v[190:193], v[222:225], v[86:89]
	v_mfma_f32_16x16x32_bf16 v[82:85], v[198:201], v[222:225], v[82:85]
	v_mfma_f32_16x16x32_bf16 v[70:73], v[190:193], v[230:233], v[70:73]
	v_mfma_f32_16x16x32_bf16 v[66:69], v[198:201], v[230:233], v[66:69]
	s_setprio 0
	s_nop 0
	s_add_i32 s46, s72, s33
	v_lshl_add_u64 v[136:137], v[136:137], 0, s[10:11]
	s_mov_b32 m0, s46
	ds_read_b128 v[202:205], v176 offset:49152
	ds_read_b128 v[206:209], v176 offset:50176
	ds_read_b128 v[210:213], v176 offset:51200
	ds_read_b128 v[214:217], v176 offset:52224
	ds_read_b128 v[218:221], v176 offset:53248
	ds_read_b128 v[222:225], v176 offset:54272
	ds_read_b128 v[226:229], v176 offset:55296
	ds_read_b128 v[230:233], v176 offset:56320
	global_load_lds_dwordx4 v[136:137], off
	s_add_i32 m0, s46, 0x2000
	s_add_u32 s44, s44, 0x40080
	v_lshl_add_u64 v[136:137], v[168:169], 0, s[10:11]
	s_addc_u32 s45, s45, 0
	s_add_i32 s46, s73, s33
	global_load_lds_dwordx4 v[136:137], off
	v_lshl_add_u64 v[136:137], s[44:45], 0, v[140:141]
	s_mov_b32 m0, s46
	s_nop 0
	global_load_lds_dwordx4 v[136:137], off
	v_lshl_add_u64 v[136:137], s[44:45], 0, v[144:145]
	s_add_i32 m0, s46, 0x2000
	s_nop 0
	global_load_lds_dwordx4 v[136:137], off
	v_lshl_add_u64 v[136:137], v[234:235], 0, s[10:11]
	s_mov_b32 m0, s57
	s_nop 0
	global_load_lds_dwordx4 v[136:137], off
	v_lshl_add_u64 v[136:137], v[236:237], 0, s[10:11]
	s_mov_b32 m0, s58
	s_nop 0
	global_load_lds_dwordx4 v[136:137], off
	s_waitcnt vmcnt(8)
	s_waitcnt lgkmcnt(0)
	s_barrier
	s_setprio 1
	v_mfma_f32_16x16x32_bf16 v[62:65], v[160:163], v[202:205], v[62:65]
	v_mfma_f32_16x16x32_bf16 v[58:61], v[178:181], v[202:205], v[58:61]
	v_mfma_f32_16x16x32_bf16 v[46:49], v[160:163], v[210:213], v[46:49]
	v_mfma_f32_16x16x32_bf16 v[42:45], v[178:181], v[210:213], v[42:45]
	v_mfma_f32_16x16x32_bf16 v[30:33], v[160:163], v[218:221], v[30:33]
	v_mfma_f32_16x16x32_bf16 v[26:29], v[178:181], v[218:221], v[26:29]
	v_mfma_f32_16x16x32_bf16 v[14:17], v[160:163], v[226:229], v[14:17]
	v_mfma_f32_16x16x32_bf16 v[10:13], v[178:181], v[226:229], v[10:13]
	v_mfma_f32_16x16x32_bf16 v[62:65], v[164:167], v[206:209], v[62:65]
	v_mfma_f32_16x16x32_bf16 v[58:61], v[182:185], v[206:209], v[58:61]
	v_mfma_f32_16x16x32_bf16 v[46:49], v[164:167], v[214:217], v[46:49]
	v_mfma_f32_16x16x32_bf16 v[42:45], v[182:185], v[214:217], v[42:45]
	v_mfma_f32_16x16x32_bf16 v[30:33], v[164:167], v[222:225], v[30:33]
	v_mfma_f32_16x16x32_bf16 v[26:29], v[182:185], v[222:225], v[26:29]
	v_mfma_f32_16x16x32_bf16 v[14:17], v[164:167], v[230:233], v[14:17]
	v_mfma_f32_16x16x32_bf16 v[10:13], v[182:185], v[230:233], v[10:13]
	v_mfma_f32_16x16x32_bf16 v[54:57], v[186:189], v[202:205], v[54:57]
	v_mfma_f32_16x16x32_bf16 v[50:53], v[194:197], v[202:205], v[50:53]
	v_mfma_f32_16x16x32_bf16 v[38:41], v[186:189], v[210:213], v[38:41]
	v_mfma_f32_16x16x32_bf16 v[34:37], v[194:197], v[210:213], v[34:37]
	v_mfma_f32_16x16x32_bf16 v[22:25], v[186:189], v[218:221], v[22:25]
	v_mfma_f32_16x16x32_bf16 v[18:21], v[194:197], v[218:221], v[18:21]
	v_mfma_f32_16x16x32_bf16 v[6:9], v[186:189], v[226:229], v[6:9]
	v_mfma_f32_16x16x32_bf16 v[2:5], v[194:197], v[226:229], v[2:5]
	v_mfma_f32_16x16x32_bf16 v[54:57], v[190:193], v[206:209], v[54:57]
	v_mfma_f32_16x16x32_bf16 v[50:53], v[198:201], v[206:209], v[50:53]
	v_mfma_f32_16x16x32_bf16 v[38:41], v[190:193], v[214:217], v[38:41]
	v_mfma_f32_16x16x32_bf16 v[34:37], v[198:201], v[214:217], v[34:37]
	s_setprio 2
	s_barrier
	v_mfma_f32_16x16x32_bf16 v[22:25], v[190:193], v[222:225], v[22:25]
	v_mfma_f32_16x16x32_bf16 v[18:21], v[198:201], v[222:225], v[18:21]
	v_mfma_f32_16x16x32_bf16 v[6:9], v[190:193], v[230:233], v[6:9]
	v_mfma_f32_16x16x32_bf16 v[2:5], v[198:201], v[230:233], v[2:5]
	s_setprio 0
	s_nop 0
	s_add_i32 s67, s67, 2
	s_add_u32 s30, s30, 0x100
	s_addc_u32 s31, s31, 0
	s_cmp_gt_u32 s67, 13
	s_cbranch_scc1 .LBB0_181
	s_branch .LBB0_179

.LBB0_944:
	s_ashr_i32 s9, s8, 31
	s_lshl_b64 s[14:15], s[8:9], 19
	s_add_u32 s14, s64, s14
	s_addc_u32 s15, s65, s15
	s_and_b64 s[16:17], s[12:13], exec
	s_cselect_b32 s9, s15, s19
	s_cselect_b32 s39, s14, s18
	s_ashr_i32 s11, s10, 31
	s_lshl_b64 s[16:17], s[10:11], 19
	v_readlane_b32 s24, v245, 3
	v_readlane_b32 s25, v245, 4
	s_add_u32 s16, s24, s16
	s_addc_u32 s17, s25, s17
	s_and_b64 s[24:25], s[12:13], exec
	s_cselect_b32 s40, s17, s23
	s_cselect_b32 s41, s16, s22
	s_lshl_b32 s11, s20, 8
	s_add_u32 s42, s22, 0x100
	v_mov_b32_e32 v2, 0
	v_or_b32_e32 v146, s11, v228
	v_lshl_add_u64 v[142:143], s[18:19], 0, v[138:139]
	v_lshl_add_u64 v[144:145], s[18:19], 0, v[140:141]
	s_addc_u32 s43, s23, 0
	s_mov_b32 s44, -2
	s_mov_b64 s[20:21], 0
	v_add_u32_e32 v147, s35, v149
	ds_read_b128 v[154:157], v147
	ds_read_b128 v[158:161], v147 offset:1024
	ds_read_b128 v[162:165], v147 offset:2048
	ds_read_b128 v[166:169], v147 offset:3072
	v_add_u32_e32 v147, s36, v149
	s_add_u32 s22, s18, s20
	ds_read_b128 v[170:173], v147
	ds_read_b128 v[174:177], v147 offset:1024
	ds_read_b128 v[178:181], v147 offset:2048
	ds_read_b128 v[182:185], v147 offset:3072
	s_addc_u32 s23, s19, s21
	s_add_u32 s22, s22, 0x100
	s_addc_u32 s23, s23, 0
	s_add_u32 s45, s42, s20
	s_addc_u32 s46, s43, s21
	s_cmpk_eq_i32 s20, 0x700
	s_cselect_b32 s25, s9, s23
	s_cselect_b32 s24, s39, s22
	s_cselect_b32 s23, s40, s46
	s_cselect_b32 s22, s41, s45
	v_lshl_add_u64 v[218:219], v[142:143], 0, s[20:21]
	s_add_i32 m0, s27, 0xc000
	ds_read_b128 v[186:189], v152
	ds_read_b128 v[190:193], v152 offset:1024
	ds_read_b128 v[194:197], v152 offset:2048
	ds_read_b128 v[198:201], v152 offset:3072
	ds_read_b128 v[202:205], v152 offset:4096
	ds_read_b128 v[206:209], v152 offset:5120
	ds_read_b128 v[210:213], v152 offset:6144
	ds_read_b128 v[214:217], v152 offset:7168
	global_load_lds_dwordx4 v[218:219], off
	v_lshl_add_u64 v[218:219], v[144:145], 0, s[20:21]
	s_add_i32 m0, s27, 0xe000
	s_nop 0
	global_load_lds_dwordx4 v[218:219], off
	s_waitcnt vmcnt(8)
	s_waitcnt lgkmcnt(0)
	s_barrier
	s_setprio 1
	v_mfma_f32_16x16x32_bf16 v[126:129], v[154:157], v[186:189], 0
	v_mfma_f32_16x16x32_bf16 v[118:121], v[162:165], v[186:189], 0
	v_mfma_f32_16x16x32_bf16 v[110:113], v[154:157], v[194:197], 0
	v_mfma_f32_16x16x32_bf16 v[102:105], v[162:165], v[194:197], 0
	v_mfma_f32_16x16x32_bf16 v[94:97], v[154:157], v[202:205], 0
	v_mfma_f32_16x16x32_bf16 v[86:89], v[162:165], v[202:205], 0
	v_mfma_f32_16x16x32_bf16 v[78:81], v[154:157], v[210:213], 0
	v_mfma_f32_16x16x32_bf16 v[70:73], v[162:165], v[210:213], 0
	v_mfma_f32_16x16x32_bf16 v[126:129], v[158:161], v[190:193], v[126:129]
	v_mfma_f32_16x16x32_bf16 v[118:121], v[166:169], v[190:193], v[118:121]
	v_mfma_f32_16x16x32_bf16 v[110:113], v[158:161], v[198:201], v[110:113]
	v_mfma_f32_16x16x32_bf16 v[102:105], v[166:169], v[198:201], v[102:105]
	v_mfma_f32_16x16x32_bf16 v[94:97], v[158:161], v[206:209], v[94:97]
	v_mfma_f32_16x16x32_bf16 v[86:89], v[166:169], v[206:209], v[86:89]
	v_mfma_f32_16x16x32_bf16 v[78:81], v[158:161], v[214:217], v[78:81]
	v_mfma_f32_16x16x32_bf16 v[70:73], v[166:169], v[214:217], v[70:73]
	v_mfma_f32_16x16x32_bf16 v[122:125], v[170:173], v[186:189], 0
	v_mfma_f32_16x16x32_bf16 v[114:117], v[178:181], v[186:189], 0
	v_mfma_f32_16x16x32_bf16 v[106:109], v[170:173], v[194:197], 0
	v_mfma_f32_16x16x32_bf16 v[98:101], v[178:181], v[194:197], 0
	v_mfma_f32_16x16x32_bf16 v[90:93], v[170:173], v[202:205], 0
	v_mfma_f32_16x16x32_bf16 v[82:85], v[178:181], v[202:205], 0
	v_mfma_f32_16x16x32_bf16 v[74:77], v[170:173], v[210:213], 0
	v_mfma_f32_16x16x32_bf16 v[66:69], v[178:181], v[210:213], 0
	v_mfma_f32_16x16x32_bf16 v[122:125], v[174:177], v[190:193], v[122:125]
	v_mfma_f32_16x16x32_bf16 v[114:117], v[182:185], v[190:193], v[114:117]
	v_mfma_f32_16x16x32_bf16 v[106:109], v[174:177], v[198:201], v[106:109]
	v_mfma_f32_16x16x32_bf16 v[98:101], v[182:185], v[198:201], v[98:101]
	s_setprio 2
	s_barrier
	v_mfma_f32_16x16x32_bf16 v[90:93], v[174:177], v[206:209], v[90:93]
	v_mfma_f32_16x16x32_bf16 v[82:85], v[182:185], v[206:209], v[82:85]
	v_mfma_f32_16x16x32_bf16 v[74:77], v[174:177], v[214:217], v[74:77]
	v_mfma_f32_16x16x32_bf16 v[66:69], v[182:185], v[214:217], v[66:69]
	s_setprio 0
	s_nop 0
	s_add_i32 s45, s35, s26
	v_lshl_add_u64 v[218:219], s[22:23], 0, v[134:135]
	s_mov_b32 m0, s45
	ds_read_b128 v[186:189], v152 offset:16384
	ds_read_b128 v[190:193], v152 offset:17408
	ds_read_b128 v[194:197], v152 offset:18432
	ds_read_b128 v[198:201], v152 offset:19456
	ds_read_b128 v[202:205], v152 offset:20480
	ds_read_b128 v[206:209], v152 offset:21504
	ds_read_b128 v[210:213], v152 offset:22528
	ds_read_b128 v[214:217], v152 offset:23552
	global_load_lds_dwordx4 v[218:219], off
	s_add_i32 m0, s45, 0x2000
	s_add_u32 s46, s22, 0x40000
	v_lshl_add_u64 v[220:221], s[22:23], 0, v[130:131]
	s_addc_u32 s47, s23, 0
	s_add_i32 s45, s36, s26
	global_load_lds_dwordx4 v[220:221], off
	v_lshl_add_u64 v[222:223], s[46:47], 0, v[134:135]
	s_mov_b32 m0, s45
	v_lshl_add_u64 v[224:225], s[24:25], 0, v[132:133]
	global_load_lds_dwordx4 v[222:223], off
	v_lshl_add_u64 v[222:223], s[46:47], 0, v[130:131]
	s_add_i32 m0, s45, 0x2000
	s_nop 0
	global_load_lds_dwordx4 v[222:223], off
	v_lshl_add_u64 v[222:223], s[24:25], 0, v[136:137]
	s_mov_b32 m0, s27
	s_nop 0
	global_load_lds_dwordx4 v[222:223], off
	s_mov_b32 m0, s28
	s_nop 0
	global_load_lds_dwordx4 v[224:225], off
	s_waitcnt vmcnt(8)
	s_waitcnt lgkmcnt(0)
	s_barrier
	s_setprio 1
	v_mfma_f32_16x16x32_bf16 v[62:65], v[154:157], v[186:189], 0
	v_mfma_f32_16x16x32_bf16 v[54:57], v[162:165], v[186:189], 0
	v_mfma_f32_16x16x32_bf16 v[46:49], v[154:157], v[194:197], 0
	v_mfma_f32_16x16x32_bf16 v[38:41], v[162:165], v[194:197], 0
	v_mfma_f32_16x16x32_bf16 v[30:33], v[154:157], v[202:205], 0
	v_mfma_f32_16x16x32_bf16 v[22:25], v[162:165], v[202:205], 0
	v_mfma_f32_16x16x32_bf16 v[14:17], v[154:157], v[210:213], 0
	v_mfma_f32_16x16x32_bf16 v[6:9], v[162:165], v[210:213], 0
	v_mfma_f32_16x16x32_bf16 v[62:65], v[158:161], v[190:193], v[62:65]
	v_mfma_f32_16x16x32_bf16 v[54:57], v[166:169], v[190:193], v[54:57]
	v_mfma_f32_16x16x32_bf16 v[46:49], v[158:161], v[198:201], v[46:49]
	v_mfma_f32_16x16x32_bf16 v[38:41], v[166:169], v[198:201], v[38:41]
	v_mfma_f32_16x16x32_bf16 v[30:33], v[158:161], v[206:209], v[30:33]
	v_mfma_f32_16x16x32_bf16 v[22:25], v[166:169], v[206:209], v[22:25]
	v_mfma_f32_16x16x32_bf16 v[14:17], v[158:161], v[214:217], v[14:17]
	v_mfma_f32_16x16x32_bf16 v[6:9], v[166:169], v[214:217], v[6:9]
	v_mfma_f32_16x16x32_bf16 v[58:61], v[170:173], v[186:189], 0
	v_mfma_f32_16x16x32_bf16 v[50:53], v[178:181], v[186:189], 0
	v_mfma_f32_16x16x32_bf16 v[42:45], v[170:173], v[194:197], 0
	v_mfma_f32_16x16x32_bf16 v[34:37], v[178:181], v[194:197], 0
	v_mfma_f32_16x16x32_bf16 v[26:29], v[170:173], v[202:205], 0
	v_mfma_f32_16x16x32_bf16 v[18:21], v[178:181], v[202:205], 0
	v_mfma_f32_16x16x32_bf16 v[10:13], v[170:173], v[210:213], 0
	v_mfma_f32_16x16x32_bf16 v[2:5], v[178:181], v[210:213], 0
	v_mfma_f32_16x16x32_bf16 v[58:61], v[174:177], v[190:193], v[58:61]
	v_mfma_f32_16x16x32_bf16 v[50:53], v[182:185], v[190:193], v[50:53]
	v_mfma_f32_16x16x32_bf16 v[42:45], v[174:177], v[198:201], v[42:45]
	v_mfma_f32_16x16x32_bf16 v[34:37], v[182:185], v[198:201], v[34:37]
	s_setprio 2
	s_barrier
	v_mfma_f32_16x16x32_bf16 v[26:29], v[174:177], v[206:209], v[26:29]
	v_mfma_f32_16x16x32_bf16 v[18:21], v[182:185], v[206:209], v[18:21]
	v_mfma_f32_16x16x32_bf16 v[10:13], v[174:177], v[214:217], v[10:13]
	v_mfma_f32_16x16x32_bf16 v[2:5], v[182:185], v[214:217], v[2:5]
	s_setprio 0
	s_nop 0
	s_add_i32 s45, 0, 0x18000
	v_add_u32_e32 v147, s45, v149
	s_add_i32 s46, 0, 0x1c000
	ds_read_b128 v[154:157], v147
	ds_read_b128 v[158:161], v147 offset:1024
	ds_read_b128 v[162:165], v147 offset:2048
	ds_read_b128 v[166:169], v147 offset:3072
	v_add_u32_e32 v147, s46, v149
	ds_read_b128 v[170:173], v147
	ds_read_b128 v[174:177], v147 offset:1024
	ds_read_b128 v[178:181], v147 offset:2048
	ds_read_b128 v[182:185], v147 offset:3072
	s_add_u32 s24, s24, 0x40000
	s_addc_u32 s25, s25, 0
	s_mov_b32 m0, s29
	v_lshl_add_u64 v[226:227], s[24:25], 0, v[136:137]
	ds_read_b128 v[186:189], v152 offset:32768
	ds_read_b128 v[190:193], v152 offset:33792
	ds_read_b128 v[194:197], v152 offset:34816
	ds_read_b128 v[198:201], v152 offset:35840
	ds_read_b128 v[202:205], v152 offset:36864
	ds_read_b128 v[206:209], v152 offset:37888
	ds_read_b128 v[210:213], v152 offset:38912
	ds_read_b128 v[214:217], v152 offset:39936
	global_load_lds_dwordx4 v[226:227], off
	v_lshl_add_u64 v[226:227], s[24:25], 0, v[132:133]
	s_mov_b32 m0, s30
	s_nop 0
	global_load_lds_dwordx4 v[226:227], off
	s_waitcnt vmcnt(8)
	s_waitcnt lgkmcnt(0)
	s_barrier
	s_setprio 1
	v_mfma_f32_16x16x32_bf16 v[126:129], v[154:157], v[186:189], v[126:129]
	v_mfma_f32_16x16x32_bf16 v[118:121], v[162:165], v[186:189], v[118:121]
	v_mfma_f32_16x16x32_bf16 v[110:113], v[154:157], v[194:197], v[110:113]
	v_mfma_f32_16x16x32_bf16 v[102:105], v[162:165], v[194:197], v[102:105]
	v_mfma_f32_16x16x32_bf16 v[94:97], v[154:157], v[202:205], v[94:97]
	v_mfma_f32_16x16x32_bf16 v[86:89], v[162:165], v[202:205], v[86:89]
	v_mfma_f32_16x16x32_bf16 v[78:81], v[154:157], v[210:213], v[78:81]
	v_mfma_f32_16x16x32_bf16 v[70:73], v[162:165], v[210:213], v[70:73]
	v_mfma_f32_16x16x32_bf16 v[126:129], v[158:161], v[190:193], v[126:129]
	v_mfma_f32_16x16x32_bf16 v[118:121], v[166:169], v[190:193], v[118:121]
	v_mfma_f32_16x16x32_bf16 v[110:113], v[158:161], v[198:201], v[110:113]
	v_mfma_f32_16x16x32_bf16 v[102:105], v[166:169], v[198:201], v[102:105]
	v_mfma_f32_16x16x32_bf16 v[94:97], v[158:161], v[206:209], v[94:97]
	v_mfma_f32_16x16x32_bf16 v[86:89], v[166:169], v[206:209], v[86:89]
	v_mfma_f32_16x16x32_bf16 v[78:81], v[158:161], v[214:217], v[78:81]
	v_mfma_f32_16x16x32_bf16 v[70:73], v[166:169], v[214:217], v[70:73]
	v_mfma_f32_16x16x32_bf16 v[122:125], v[170:173], v[186:189], v[122:125]
	v_mfma_f32_16x16x32_bf16 v[114:117], v[178:181], v[186:189], v[114:117]
	v_mfma_f32_16x16x32_bf16 v[106:109], v[170:173], v[194:197], v[106:109]
	v_mfma_f32_16x16x32_bf16 v[98:101], v[178:181], v[194:197], v[98:101]
	v_mfma_f32_16x16x32_bf16 v[90:93], v[170:173], v[202:205], v[90:93]
	v_mfma_f32_16x16x32_bf16 v[82:85], v[178:181], v[202:205], v[82:85]
	v_mfma_f32_16x16x32_bf16 v[74:77], v[170:173], v[210:213], v[74:77]
	v_mfma_f32_16x16x32_bf16 v[66:69], v[178:181], v[210:213], v[66:69]
	v_mfma_f32_16x16x32_bf16 v[122:125], v[174:177], v[190:193], v[122:125]
	v_mfma_f32_16x16x32_bf16 v[114:117], v[182:185], v[190:193], v[114:117]
	v_mfma_f32_16x16x32_bf16 v[106:109], v[174:177], v[198:201], v[106:109]
	v_mfma_f32_16x16x32_bf16 v[98:101], v[182:185], v[198:201], v[98:101]
	s_setprio 2
	s_barrier
	v_mfma_f32_16x16x32_bf16 v[90:93], v[174:177], v[206:209], v[90:93]
	v_mfma_f32_16x16x32_bf16 v[82:85], v[182:185], v[206:209], v[82:85]
	v_mfma_f32_16x16x32_bf16 v[74:77], v[174:177], v[214:217], v[74:77]
	v_mfma_f32_16x16x32_bf16 v[66:69], v[182:185], v[214:217], v[66:69]
	s_setprio 0
	s_nop 0
	s_add_i32 s24, s45, s26
	v_lshl_add_u64 v[218:219], v[218:219], 0, s[2:3]
	s_mov_b32 m0, s24
	ds_read_b128 v[186:189], v152 offset:49152
	ds_read_b128 v[190:193], v152 offset:50176
	ds_read_b128 v[194:197], v152 offset:51200
	ds_read_b128 v[198:201], v152 offset:52224
	ds_read_b128 v[202:205], v152 offset:53248
	ds_read_b128 v[206:209], v152 offset:54272
	ds_read_b128 v[210:213], v152 offset:55296
	ds_read_b128 v[214:217], v152 offset:56320
	global_load_lds_dwordx4 v[218:219], off
	s_add_i32 m0, s24, 0x2000
	s_add_u32 s22, s22, 0x40080
	v_lshl_add_u64 v[218:219], v[220:221], 0, s[2:3]
	s_addc_u32 s23, s23, 0
	s_add_i32 s24, s46, s26
	global_load_lds_dwordx4 v[218:219], off
	v_lshl_add_u64 v[218:219], s[22:23], 0, v[134:135]
	s_mov_b32 m0, s24
	s_nop 0
	global_load_lds_dwordx4 v[218:219], off
	v_lshl_add_u64 v[218:219], s[22:23], 0, v[130:131]
	s_add_i32 m0, s24, 0x2000
	s_nop 0
	global_load_lds_dwordx4 v[218:219], off
	v_lshl_add_u64 v[218:219], v[222:223], 0, s[2:3]
	s_mov_b32 m0, s33
	s_nop 0
	global_load_lds_dwordx4 v[218:219], off
	v_lshl_add_u64 v[218:219], v[224:225], 0, s[2:3]
	s_mov_b32 m0, s34
	s_nop 0
	global_load_lds_dwordx4 v[218:219], off
	s_waitcnt vmcnt(8)
	s_waitcnt lgkmcnt(0)
	s_barrier
	s_setprio 1
	v_mfma_f32_16x16x32_bf16 v[62:65], v[154:157], v[186:189], v[62:65]
	v_mfma_f32_16x16x32_bf16 v[54:57], v[162:165], v[186:189], v[54:57]
	v_mfma_f32_16x16x32_bf16 v[46:49], v[154:157], v[194:197], v[46:49]
	v_mfma_f32_16x16x32_bf16 v[38:41], v[162:165], v[194:197], v[38:41]
	v_mfma_f32_16x16x32_bf16 v[30:33], v[154:157], v[202:205], v[30:33]
	v_mfma_f32_16x16x32_bf16 v[22:25], v[162:165], v[202:205], v[22:25]
	v_mfma_f32_16x16x32_bf16 v[14:17], v[154:157], v[210:213], v[14:17]
	v_mfma_f32_16x16x32_bf16 v[6:9], v[162:165], v[210:213], v[6:9]
	v_mfma_f32_16x16x32_bf16 v[62:65], v[158:161], v[190:193], v[62:65]
	v_mfma_f32_16x16x32_bf16 v[54:57], v[166:169], v[190:193], v[54:57]
	v_mfma_f32_16x16x32_bf16 v[46:49], v[158:161], v[198:201], v[46:49]
	v_mfma_f32_16x16x32_bf16 v[38:41], v[166:169], v[198:201], v[38:41]
	v_mfma_f32_16x16x32_bf16 v[30:33], v[158:161], v[206:209], v[30:33]
	v_mfma_f32_16x16x32_bf16 v[22:25], v[166:169], v[206:209], v[22:25]
	v_mfma_f32_16x16x32_bf16 v[14:17], v[158:161], v[214:217], v[14:17]
	v_mfma_f32_16x16x32_bf16 v[6:9], v[166:169], v[214:217], v[6:9]
	v_mfma_f32_16x16x32_bf16 v[58:61], v[170:173], v[186:189], v[58:61]
	v_mfma_f32_16x16x32_bf16 v[50:53], v[178:181], v[186:189], v[50:53]
	v_mfma_f32_16x16x32_bf16 v[42:45], v[170:173], v[194:197], v[42:45]
	v_mfma_f32_16x16x32_bf16 v[34:37], v[178:181], v[194:197], v[34:37]
	v_mfma_f32_16x16x32_bf16 v[26:29], v[170:173], v[202:205], v[26:29]
	v_mfma_f32_16x16x32_bf16 v[18:21], v[178:181], v[202:205], v[18:21]
	v_mfma_f32_16x16x32_bf16 v[10:13], v[170:173], v[210:213], v[10:13]
	v_mfma_f32_16x16x32_bf16 v[2:5], v[178:181], v[210:213], v[2:5]
	v_mfma_f32_16x16x32_bf16 v[58:61], v[174:177], v[190:193], v[58:61]
	v_mfma_f32_16x16x32_bf16 v[50:53], v[182:185], v[190:193], v[50:53]
	v_mfma_f32_16x16x32_bf16 v[42:45], v[174:177], v[198:201], v[42:45]
	v_mfma_f32_16x16x32_bf16 v[34:37], v[182:185], v[198:201], v[34:37]
	s_setprio 2
	s_barrier
	v_mfma_f32_16x16x32_bf16 v[26:29], v[174:177], v[206:209], v[26:29]
	v_mfma_f32_16x16x32_bf16 v[18:21], v[182:185], v[206:209], v[18:21]
	v_mfma_f32_16x16x32_bf16 v[10:13], v[174:177], v[214:217], v[10:13]
	v_mfma_f32_16x16x32_bf16 v[2:5], v[182:185], v[214:217], v[2:5]
	s_setprio 0
	s_nop 0
	s_add_i32 s44, s44, 2
	s_add_u32 s20, s20, 0x100
	s_addc_u32 s21, s21, 0
	s_cmp_gt_u32 s44, 13
	s_cbranch_scc1 .LBB0_948
	s_branch .LBB0_946

.LBB0_1017:
	v_lshl_add_u64 v[14:15], s[14:15], 0, v[130:131]
	v_lshl_add_u64 v[16:17], s[14:15], 0, v[134:135]
	s_add_i32 m0, s50, 0x18000
	v_lshl_add_u64 v[14:15], v[14:15], 0, s[24:25]
	s_waitcnt vmcnt(2)
	s_barrier
	global_load_lds_dwordx4 v[14:15], off
	v_lshl_add_u64 v[14:15], v[16:17], 0, s[24:25]
	s_add_i32 m0, s50, 0x1a000
	s_add_i32 s54, s50, 0x8000
	global_load_lds_dwordx4 v[14:15], off
	v_lshl_add_u64 v[4:5], v[4:5], 0, s[24:25]
	s_mov_b32 m0, s54
	s_add_i32 s55, s50, 0xa000
	global_load_lds_dwordx4 v[4:5], off
	v_lshl_add_u64 v[2:3], v[2:3], 0, s[24:25]
	s_mov_b32 m0, s55
	v_and_b32_e32 v212, 15, v211
	global_load_lds_dwordx4 v[2:3], off
	s_add_i32 m0, s50, 0x1c000
	v_lshl_add_u64 v[2:3], s[18:19], 0, v[130:131]
	global_load_lds_dwordx4 v[2:3], off
	v_lshl_add_u64 v[2:3], s[18:19], 0, v[134:135]
	s_add_i32 m0, s50, 0x1e000
	v_and_b32_e32 v18, 48, v211
	global_load_lds_dwordx4 v[2:3], off
	v_lshlrev_b32_e32 v19, 2, v211
	s_and_b32 s38, s34, 3
	s_lshl_b32 s4, s35, 13
	v_lshl_or_b32 v18, v212, 6, v18
	v_and_b32_e32 v19, 32, v19
	v_bitop3_b32 v20, v18, s4, v19 bitop3:0xde
	s_lshl_b32 s4, s38, 12
	s_add_u32 s56, s42, s3
	s_addc_u32 s57, s43, s2
	v_bitop3_b32 v140, v18, s4, v19 bitop3:0xde
	s_add_u32 s4, s44, s3
	v_lshrrev_b32_e32 v3, 1, v11
	v_mul_lo_u32 v2, v10, s46
	s_addc_u32 s5, s45, s2
	v_mad_u64_u32 v[2:3], s[2:3], v3, s47, v[2:3]
	v_or_b32_e32 v2, v2, v12
	v_add_lshl_u32 v2, v2, v13, 1
	v_mov_b32_e32 v3, v131
	v_lshl_add_u64 v[136:137], s[4:5], 0, v[2:3]
	v_lshrrev_b32_e32 v3, 1, v6
	v_mul_lo_u32 v2, v7, s46
	v_mad_u64_u32 v[2:3], s[2:3], v3, s47, v[2:3]
	v_or_b32_e32 v2, v2, v8
	s_waitcnt vmcnt(6)
	v_add_lshl_u32 v2, v2, v9, 1
	v_mov_b32_e32 v3, v131
	v_lshl_add_u64 v[138:139], s[4:5], 0, v[2:3]
	v_mov_b32_e32 v2, 0
	v_lshl_or_b32 v210, s35, 6, v212
	s_mov_b32 s58, -2
	v_add_u32_e32 v141, 0, v20
	s_mov_b64 s[2:3], s[22:23]
	s_barrier
	s_add_u32 s4, s70, s56
	s_addc_u32 s5, s71, s57
	s_add_u32 s59, s70, s2
	s_addc_u32 s60, s71, s3
	s_add_i32 s61, 0, 0x10000
	s_cmp_eq_u32 s58, 40
	s_cselect_b32 s31, s1, s5
	s_cselect_b32 s30, s0, s4
	s_cselect_b32 s5, s15, s60
	s_cselect_b32 s4, s14, s59
	s_add_i32 s59, 0, 0x14000
	v_add_u32_e32 v154, s61, v140
	v_add_u32_e32 v170, s59, v140
	ds_read_b128 v[142:145], v154
	ds_read_b128 v[146:149], v154 offset:1024
	ds_read_b128 v[150:153], v154 offset:2048
	ds_read_b128 v[154:157], v154 offset:3072
	ds_read_b128 v[158:161], v170
	ds_read_b128 v[162:165], v170 offset:1024
	ds_read_b128 v[166:169], v170 offset:2048
	ds_read_b128 v[170:173], v170 offset:3072
	v_lshl_add_u64 v[214:215], s[70:71], 0, v[136:137]
	s_add_i32 m0, s50, 0xc000
	ds_read_b128 v[174:177], v141
	ds_read_b128 v[178:181], v141 offset:1024
	ds_read_b128 v[182:185], v141 offset:2048
	ds_read_b128 v[186:189], v141 offset:3072
	ds_read_b128 v[190:193], v141 offset:4096
	ds_read_b128 v[194:197], v141 offset:5120
	ds_read_b128 v[198:201], v141 offset:6144
	ds_read_b128 v[202:205], v141 offset:7168
	global_load_lds_dwordx4 v[214:215], off
	v_lshl_add_u64 v[214:215], s[70:71], 0, v[138:139]
	s_add_i32 m0, s50, 0xe000
	s_nop 0
	global_load_lds_dwordx4 v[214:215], off
	s_waitcnt vmcnt(8)
	s_waitcnt lgkmcnt(0)
	s_barrier
	s_setprio 1
	v_mfma_f32_16x16x32_bf16 v[126:129], v[142:145], v[174:177], 0
	v_mfma_f32_16x16x32_bf16 v[122:125], v[150:153], v[174:177], 0
	v_mfma_f32_16x16x32_bf16 v[110:113], v[142:145], v[182:185], 0
	v_mfma_f32_16x16x32_bf16 v[106:109], v[150:153], v[182:185], 0
	v_mfma_f32_16x16x32_bf16 v[94:97], v[142:145], v[190:193], 0
	v_mfma_f32_16x16x32_bf16 v[90:93], v[150:153], v[190:193], 0
	v_mfma_f32_16x16x32_bf16 v[78:81], v[142:145], v[198:201], 0
	v_mfma_f32_16x16x32_bf16 v[74:77], v[150:153], v[198:201], 0
	v_mfma_f32_16x16x32_bf16 v[126:129], v[146:149], v[178:181], v[126:129]
	v_mfma_f32_16x16x32_bf16 v[122:125], v[154:157], v[178:181], v[122:125]
	v_mfma_f32_16x16x32_bf16 v[110:113], v[146:149], v[186:189], v[110:113]
	v_mfma_f32_16x16x32_bf16 v[106:109], v[154:157], v[186:189], v[106:109]
	v_mfma_f32_16x16x32_bf16 v[94:97], v[146:149], v[194:197], v[94:97]
	v_mfma_f32_16x16x32_bf16 v[90:93], v[154:157], v[194:197], v[90:93]
	v_mfma_f32_16x16x32_bf16 v[78:81], v[146:149], v[202:205], v[78:81]
	v_mfma_f32_16x16x32_bf16 v[74:77], v[154:157], v[202:205], v[74:77]
	v_mfma_f32_16x16x32_bf16 v[118:121], v[158:161], v[174:177], 0
	v_mfma_f32_16x16x32_bf16 v[114:117], v[166:169], v[174:177], 0
	v_mfma_f32_16x16x32_bf16 v[102:105], v[158:161], v[182:185], 0
	v_mfma_f32_16x16x32_bf16 v[98:101], v[166:169], v[182:185], 0
	v_mfma_f32_16x16x32_bf16 v[86:89], v[158:161], v[190:193], 0
	v_mfma_f32_16x16x32_bf16 v[82:85], v[166:169], v[190:193], 0
	v_mfma_f32_16x16x32_bf16 v[70:73], v[158:161], v[198:201], 0
	v_mfma_f32_16x16x32_bf16 v[66:69], v[166:169], v[198:201], 0
	v_mfma_f32_16x16x32_bf16 v[118:121], v[162:165], v[178:181], v[118:121]
	v_mfma_f32_16x16x32_bf16 v[114:117], v[170:173], v[178:181], v[114:117]
	v_mfma_f32_16x16x32_bf16 v[102:105], v[162:165], v[186:189], v[102:105]
	v_mfma_f32_16x16x32_bf16 v[98:101], v[170:173], v[186:189], v[98:101]
	s_setprio 2
	s_barrier
	v_mfma_f32_16x16x32_bf16 v[86:89], v[162:165], v[194:197], v[86:89]
	v_mfma_f32_16x16x32_bf16 v[82:85], v[170:173], v[194:197], v[82:85]
	v_mfma_f32_16x16x32_bf16 v[70:73], v[162:165], v[202:205], v[70:73]
	v_mfma_f32_16x16x32_bf16 v[66:69], v[170:173], v[202:205], v[66:69]
	s_setprio 0
	s_nop 0
	s_add_i32 s60, s61, s39
	v_lshl_add_u64 v[214:215], s[4:5], 0, v[130:131]
	s_mov_b32 m0, s60
	ds_read_b128 v[174:177], v141 offset:16384
	ds_read_b128 v[178:181], v141 offset:17408
	ds_read_b128 v[182:185], v141 offset:18432
	ds_read_b128 v[186:189], v141 offset:19456
	ds_read_b128 v[190:193], v141 offset:20480
	ds_read_b128 v[194:197], v141 offset:21504
	ds_read_b128 v[198:201], v141 offset:22528
	ds_read_b128 v[202:205], v141 offset:23552
	global_load_lds_dwordx4 v[214:215], off
	s_add_i32 m0, s60, 0x2000
	s_add_u32 s60, s4, 0xb0000
	v_lshl_add_u64 v[216:217], s[4:5], 0, v[134:135]
	s_addc_u32 s61, s5, 0
	s_add_i32 s59, s59, s39
	global_load_lds_dwordx4 v[216:217], off
	v_lshl_add_u64 v[218:219], s[60:61], 0, v[130:131]
	s_mov_b32 m0, s59
	v_lshl_add_u64 v[220:221], s[30:31], 0, v[134:135]
	global_load_lds_dwordx4 v[218:219], off
	v_lshl_add_u64 v[218:219], s[60:61], 0, v[134:135]
	s_add_i32 m0, s59, 0x2000
	s_nop 0
	global_load_lds_dwordx4 v[218:219], off
	v_lshl_add_u64 v[218:219], s[30:31], 0, v[130:131]
	s_mov_b32 m0, s50
	s_nop 0
	global_load_lds_dwordx4 v[218:219], off
	s_mov_b32 m0, s51
	s_nop 0
	global_load_lds_dwordx4 v[220:221], off
	s_waitcnt vmcnt(8)
	s_waitcnt lgkmcnt(0)
	s_barrier
	s_setprio 1
	v_mfma_f32_16x16x32_bf16 v[62:65], v[142:145], v[174:177], 0
	v_mfma_f32_16x16x32_bf16 v[58:61], v[150:153], v[174:177], 0
	v_mfma_f32_16x16x32_bf16 v[46:49], v[142:145], v[182:185], 0
	v_mfma_f32_16x16x32_bf16 v[42:45], v[150:153], v[182:185], 0
	v_mfma_f32_16x16x32_bf16 v[30:33], v[142:145], v[190:193], 0
	v_mfma_f32_16x16x32_bf16 v[26:29], v[150:153], v[190:193], 0
	v_mfma_f32_16x16x32_bf16 v[14:17], v[142:145], v[198:201], 0
	v_mfma_f32_16x16x32_bf16 v[10:13], v[150:153], v[198:201], 0
	v_mfma_f32_16x16x32_bf16 v[62:65], v[146:149], v[178:181], v[62:65]
	v_mfma_f32_16x16x32_bf16 v[58:61], v[154:157], v[178:181], v[58:61]
	v_mfma_f32_16x16x32_bf16 v[46:49], v[146:149], v[186:189], v[46:49]
	v_mfma_f32_16x16x32_bf16 v[42:45], v[154:157], v[186:189], v[42:45]
	v_mfma_f32_16x16x32_bf16 v[30:33], v[146:149], v[194:197], v[30:33]
	v_mfma_f32_16x16x32_bf16 v[26:29], v[154:157], v[194:197], v[26:29]
	v_mfma_f32_16x16x32_bf16 v[14:17], v[146:149], v[202:205], v[14:17]
	v_mfma_f32_16x16x32_bf16 v[10:13], v[154:157], v[202:205], v[10:13]
	v_mfma_f32_16x16x32_bf16 v[54:57], v[158:161], v[174:177], 0
	v_mfma_f32_16x16x32_bf16 v[50:53], v[166:169], v[174:177], 0
	v_mfma_f32_16x16x32_bf16 v[38:41], v[158:161], v[182:185], 0
	v_mfma_f32_16x16x32_bf16 v[34:37], v[166:169], v[182:185], 0
	v_mfma_f32_16x16x32_bf16 v[22:25], v[158:161], v[190:193], 0
	v_mfma_f32_16x16x32_bf16 v[18:21], v[166:169], v[190:193], 0
	v_mfma_f32_16x16x32_bf16 v[6:9], v[158:161], v[198:201], 0
	v_mfma_f32_16x16x32_bf16 v[2:5], v[166:169], v[198:201], 0
	v_mfma_f32_16x16x32_bf16 v[54:57], v[162:165], v[178:181], v[54:57]
	v_mfma_f32_16x16x32_bf16 v[50:53], v[170:173], v[178:181], v[50:53]
	v_mfma_f32_16x16x32_bf16 v[38:41], v[162:165], v[186:189], v[38:41]
	v_mfma_f32_16x16x32_bf16 v[34:37], v[170:173], v[186:189], v[34:37]
	s_setprio 2
	s_barrier
	v_mfma_f32_16x16x32_bf16 v[22:25], v[162:165], v[194:197], v[22:25]
	v_mfma_f32_16x16x32_bf16 v[18:21], v[170:173], v[194:197], v[18:21]
	v_mfma_f32_16x16x32_bf16 v[6:9], v[162:165], v[202:205], v[6:9]
	v_mfma_f32_16x16x32_bf16 v[2:5], v[170:173], v[202:205], v[2:5]
	s_setprio 0
	s_nop 0
	s_add_i32 s59, 0, 0x18000
	s_add_i32 s60, 0, 0x1c000
	v_add_u32_e32 v154, s59, v140
	v_add_u32_e32 v170, s60, v140
	ds_read_b128 v[142:145], v154
	ds_read_b128 v[146:149], v154 offset:1024
	ds_read_b128 v[150:153], v154 offset:2048
	ds_read_b128 v[154:157], v154 offset:3072
	ds_read_b128 v[158:161], v170
	ds_read_b128 v[162:165], v170 offset:1024
	ds_read_b128 v[166:169], v170 offset:2048
	ds_read_b128 v[170:173], v170 offset:3072
	s_add_u32 s30, s30, 0xb0000
	s_addc_u32 s31, s31, 0
	s_mov_b32 m0, s52
	v_lshl_add_u64 v[222:223], s[30:31], 0, v[130:131]
	ds_read_b128 v[174:177], v141 offset:32768
	ds_read_b128 v[178:181], v141 offset:33792
	ds_read_b128 v[182:185], v141 offset:34816
	ds_read_b128 v[186:189], v141 offset:35840
	ds_read_b128 v[190:193], v141 offset:36864
	ds_read_b128 v[194:197], v141 offset:37888
	ds_read_b128 v[198:201], v141 offset:38912
	ds_read_b128 v[202:205], v141 offset:39936
	global_load_lds_dwordx4 v[222:223], off
	v_lshl_add_u64 v[222:223], s[30:31], 0, v[134:135]
	s_mov_b32 m0, s53
	s_nop 0
	global_load_lds_dwordx4 v[222:223], off
	s_waitcnt vmcnt(8)
	s_waitcnt lgkmcnt(0)
	s_barrier
	s_setprio 1
	v_mfma_f32_16x16x32_bf16 v[126:129], v[142:145], v[174:177], v[126:129]
	v_mfma_f32_16x16x32_bf16 v[122:125], v[150:153], v[174:177], v[122:125]
	v_mfma_f32_16x16x32_bf16 v[110:113], v[142:145], v[182:185], v[110:113]
	v_mfma_f32_16x16x32_bf16 v[106:109], v[150:153], v[182:185], v[106:109]
	v_mfma_f32_16x16x32_bf16 v[94:97], v[142:145], v[190:193], v[94:97]
	v_mfma_f32_16x16x32_bf16 v[90:93], v[150:153], v[190:193], v[90:93]
	v_mfma_f32_16x16x32_bf16 v[78:81], v[142:145], v[198:201], v[78:81]
	v_mfma_f32_16x16x32_bf16 v[74:77], v[150:153], v[198:201], v[74:77]
	v_mfma_f32_16x16x32_bf16 v[126:129], v[146:149], v[178:181], v[126:129]
	v_mfma_f32_16x16x32_bf16 v[122:125], v[154:157], v[178:181], v[122:125]
	v_mfma_f32_16x16x32_bf16 v[110:113], v[146:149], v[186:189], v[110:113]
	v_mfma_f32_16x16x32_bf16 v[106:109], v[154:157], v[186:189], v[106:109]
	v_mfma_f32_16x16x32_bf16 v[94:97], v[146:149], v[194:197], v[94:97]
	v_mfma_f32_16x16x32_bf16 v[90:93], v[154:157], v[194:197], v[90:93]
	v_mfma_f32_16x16x32_bf16 v[78:81], v[146:149], v[202:205], v[78:81]
	v_mfma_f32_16x16x32_bf16 v[74:77], v[154:157], v[202:205], v[74:77]
	v_mfma_f32_16x16x32_bf16 v[118:121], v[158:161], v[174:177], v[118:121]
	v_mfma_f32_16x16x32_bf16 v[114:117], v[166:169], v[174:177], v[114:117]
	v_mfma_f32_16x16x32_bf16 v[102:105], v[158:161], v[182:185], v[102:105]
	v_mfma_f32_16x16x32_bf16 v[98:101], v[166:169], v[182:185], v[98:101]
	v_mfma_f32_16x16x32_bf16 v[86:89], v[158:161], v[190:193], v[86:89]
	v_mfma_f32_16x16x32_bf16 v[82:85], v[166:169], v[190:193], v[82:85]
	v_mfma_f32_16x16x32_bf16 v[70:73], v[158:161], v[198:201], v[70:73]
	v_mfma_f32_16x16x32_bf16 v[66:69], v[166:169], v[198:201], v[66:69]
	v_mfma_f32_16x16x32_bf16 v[118:121], v[162:165], v[178:181], v[118:121]
	v_mfma_f32_16x16x32_bf16 v[114:117], v[170:173], v[178:181], v[114:117]
	v_mfma_f32_16x16x32_bf16 v[102:105], v[162:165], v[186:189], v[102:105]
	v_mfma_f32_16x16x32_bf16 v[98:101], v[170:173], v[186:189], v[98:101]
	s_setprio 2
	s_barrier
	v_mfma_f32_16x16x32_bf16 v[86:89], v[162:165], v[194:197], v[86:89]
	v_mfma_f32_16x16x32_bf16 v[82:85], v[170:173], v[194:197], v[82:85]
	v_mfma_f32_16x16x32_bf16 v[70:73], v[162:165], v[202:205], v[70:73]
	v_mfma_f32_16x16x32_bf16 v[66:69], v[170:173], v[202:205], v[66:69]
	s_setprio 0
	s_nop 0
	s_add_i32 s30, s59, s39
	v_lshl_add_u64 v[214:215], v[214:215], 0, s[24:25]
	s_mov_b32 m0, s30
	ds_read_b128 v[174:177], v141 offset:49152
	ds_read_b128 v[178:181], v141 offset:50176
	ds_read_b128 v[182:185], v141 offset:51200
	ds_read_b128 v[186:189], v141 offset:52224
	ds_read_b128 v[190:193], v141 offset:53248
	ds_read_b128 v[194:197], v141 offset:54272
	ds_read_b128 v[198:201], v141 offset:55296
	ds_read_b128 v[202:205], v141 offset:56320
	global_load_lds_dwordx4 v[214:215], off
	s_add_i32 m0, s30, 0x2000
	s_add_u32 s4, s4, 0xb0080
	v_lshl_add_u64 v[214:215], v[216:217], 0, s[24:25]
	s_addc_u32 s5, s5, 0
	s_add_i32 s30, s60, s39
	global_load_lds_dwordx4 v[214:215], off
	v_lshl_add_u64 v[214:215], s[4:5], 0, v[130:131]
	s_mov_b32 m0, s30
	s_nop 0
	global_load_lds_dwordx4 v[214:215], off
	v_lshl_add_u64 v[214:215], s[4:5], 0, v[134:135]
	s_add_i32 m0, s30, 0x2000
	s_nop 0
	global_load_lds_dwordx4 v[214:215], off
	v_lshl_add_u64 v[214:215], v[218:219], 0, s[24:25]
	s_mov_b32 m0, s54
	s_nop 0
	global_load_lds_dwordx4 v[214:215], off
	v_lshl_add_u64 v[214:215], v[220:221], 0, s[24:25]
	s_mov_b32 m0, s55
	s_nop 0
	global_load_lds_dwordx4 v[214:215], off
	s_waitcnt vmcnt(8)
	s_waitcnt lgkmcnt(0)
	s_barrier
	s_setprio 1
	v_mfma_f32_16x16x32_bf16 v[62:65], v[142:145], v[174:177], v[62:65]
	v_mfma_f32_16x16x32_bf16 v[58:61], v[150:153], v[174:177], v[58:61]
	v_mfma_f32_16x16x32_bf16 v[46:49], v[142:145], v[182:185], v[46:49]
	v_mfma_f32_16x16x32_bf16 v[42:45], v[150:153], v[182:185], v[42:45]
	v_mfma_f32_16x16x32_bf16 v[30:33], v[142:145], v[190:193], v[30:33]
	v_mfma_f32_16x16x32_bf16 v[26:29], v[150:153], v[190:193], v[26:29]
	v_mfma_f32_16x16x32_bf16 v[14:17], v[142:145], v[198:201], v[14:17]
	v_mfma_f32_16x16x32_bf16 v[10:13], v[150:153], v[198:201], v[10:13]
	v_mfma_f32_16x16x32_bf16 v[62:65], v[146:149], v[178:181], v[62:65]
	v_mfma_f32_16x16x32_bf16 v[58:61], v[154:157], v[178:181], v[58:61]
	v_mfma_f32_16x16x32_bf16 v[46:49], v[146:149], v[186:189], v[46:49]
	v_mfma_f32_16x16x32_bf16 v[42:45], v[154:157], v[186:189], v[42:45]
	v_mfma_f32_16x16x32_bf16 v[30:33], v[146:149], v[194:197], v[30:33]
	v_mfma_f32_16x16x32_bf16 v[26:29], v[154:157], v[194:197], v[26:29]
	v_mfma_f32_16x16x32_bf16 v[14:17], v[146:149], v[202:205], v[14:17]
	v_mfma_f32_16x16x32_bf16 v[10:13], v[154:157], v[202:205], v[10:13]
	v_mfma_f32_16x16x32_bf16 v[54:57], v[158:161], v[174:177], v[54:57]
	v_mfma_f32_16x16x32_bf16 v[50:53], v[166:169], v[174:177], v[50:53]
	v_mfma_f32_16x16x32_bf16 v[38:41], v[158:161], v[182:185], v[38:41]
	v_mfma_f32_16x16x32_bf16 v[34:37], v[166:169], v[182:185], v[34:37]
	v_mfma_f32_16x16x32_bf16 v[22:25], v[158:161], v[190:193], v[22:25]
	v_mfma_f32_16x16x32_bf16 v[18:21], v[166:169], v[190:193], v[18:21]
	v_mfma_f32_16x16x32_bf16 v[6:9], v[158:161], v[198:201], v[6:9]
	v_mfma_f32_16x16x32_bf16 v[2:5], v[166:169], v[198:201], v[2:5]
	v_mfma_f32_16x16x32_bf16 v[54:57], v[162:165], v[178:181], v[54:57]
	v_mfma_f32_16x16x32_bf16 v[50:53], v[170:173], v[178:181], v[50:53]
	v_mfma_f32_16x16x32_bf16 v[38:41], v[162:165], v[186:189], v[38:41]
	v_mfma_f32_16x16x32_bf16 v[34:37], v[170:173], v[186:189], v[34:37]
	s_setprio 2
	s_barrier
	v_mfma_f32_16x16x32_bf16 v[22:25], v[162:165], v[194:197], v[22:25]
	v_mfma_f32_16x16x32_bf16 v[18:21], v[170:173], v[194:197], v[18:21]
	v_mfma_f32_16x16x32_bf16 v[6:9], v[162:165], v[202:205], v[6:9]
	v_mfma_f32_16x16x32_bf16 v[2:5], v[170:173], v[202:205], v[2:5]
	s_setprio 0
	s_nop 0
	s_add_i32 s58, s58, 2
	s_add_u32 s56, s56, 0x100
	s_addc_u32 s57, s57, 0
	s_add_u32 s2, s2, 0x100
	s_addc_u32 s3, s3, 0
	v_lshl_add_u64 v[136:137], v[136:137], 0, s[28:29]
	s_cmp_lt_u32 s58, 42
	v_lshl_add_u64 v[138:139], v[138:139], 0, s[28:29]
